# P2a spatial V staging: second-pass V load and norm-gain loads issued behind the first-pass load
# baseline (speedup 1.0000x reference)
.LBB0_294:
	s_ashr_i32 s0, s58, 2
	s_ashr_i32 s1, s0, 31
	s_lshl_b64 s[38:39], s[0:1], 7
	v_lshl_add_u64 v[2:3], s[38:39], 0, v[18:19]
	v_mov_b64_e32 v[10:11], s[36:37]
	s_lshl_b32 s52, s59, 8
	v_mad_u64_u32 v[4:5], s[0:1], v2, s75, v[10:11]
	v_lshl_add_u64 v[6:7], v[30:31], 0, s[52:53]
	v_mad_i32_i24 v5, v3, s75, v5
	s_lshl_b32 s52, s59, 7
	v_lshl_add_u64 v[2:3], v[4:5], 0, s[52:53]
	v_lshl_add_u64 v[2:3], v[2:3], 0, v[0:1]
	v_add_co_u32_e32 v2, vcc, s41, v2
	s_mov_b32 s40, 0xf800000
	s_nop 0
	v_addc_co_u32_e32 v3, vcc, 0, v3, vcc
	global_load_dwordx4 v[2:5], v[2:3], off offset:2560
	v_lshl_add_u64 v[80:81], s[38:39], 0, v[36:37]
	v_mad_u64_u32 v[82:83], s[0:1], v80, s75, v[10:11]
	v_mad_i32_i24 v83, v81, s75, v83
	v_lshl_add_u64 v[82:83], v[82:83], 0, s[52:53]
	v_lshl_add_u64 v[82:83], v[82:83], 0, v[0:1]
	v_add_co_u32_e32 v82, vcc, s41, v82
	s_nop 1
	v_addc_co_u32_e32 v83, vcc, 0, v83, vcc
	global_load_dwordx4 v[84:87], v[82:83], off offset:2560
	global_load_dwordx4 v[88:91], v[6:7], off offset:16
	global_load_dwordx4 v[92:95], v[6:7], off
	s_movk_i32 s61, 0x7fff
	v_mov_b32_e32 v17, 0
	s_waitcnt vmcnt(0)
	v_lshlrev_b32_e32 v9, 16, v3
	v_lshlrev_b32_e32 v8, 16, v2
	v_and_b32_e32 v3, 0xffff0000, v3
	v_and_b32_e32 v2, 0xffff0000, v2
	v_pk_mul_f32 v[12:13], v[2:3], v[2:3]
	v_and_b32_e32 v41, 0xffff0000, v5
	v_and_b32_e32 v40, 0xffff0000, v4
	v_pk_fma_f32 v[12:13], v[8:9], v[8:9], v[12:13]
	v_lshlrev_b32_e32 v15, 16, v5
	v_lshlrev_b32_e32 v14, 16, v4
	v_pk_mul_f32 v[4:5], v[40:41], v[40:41]
	v_add_f32_e32 v12, v12, v13
	v_pk_fma_f32 v[4:5], v[14:15], v[14:15], v[4:5]
	v_mov_b32_e32 v58, v15
	v_add_f32_e32 v4, v4, v12
	v_add_f32_e32 v4, v5, v4
	ds_bpermute_b32 v5, v44, v4
	v_mov_b32_e32 v59, v41
	v_mov_b32_e32 v15, v40
	s_waitcnt lgkmcnt(0)
	v_add_f32_e32 v4, v4, v5
	ds_bpermute_b32 v5, v45, v4
	s_waitcnt lgkmcnt(0)
	v_add_f32_e32 v4, v4, v5
	ds_bpermute_b32 v5, v46, v4
	s_waitcnt lgkmcnt(0)
	v_add_f32_e32 v4, v4, v5
	v_fmamk_f32 v4, v4, 0x3c800000, v198
	v_cmp_gt_f32_e64 s[0:1], s40, v4
	v_mul_f32_e32 v5, 0x4f800000, v4
	s_nop 0
	v_cndmask_b32_e64 v4, v4, v5, s[0:1]
	v_sqrt_f32_e32 v5, v4
	s_nop 0
	v_add_u32_e32 v12, -1, v5
	v_fma_f32 v13, -v12, v5, v4
	v_cmp_ge_f32_e32 vcc, 0, v13
	v_add_u32_e32 v13, 1, v5
	s_nop 0
	v_cndmask_b32_e32 v12, v5, v12, vcc
	v_fma_f32 v5, -v13, v5, v4
	v_cmp_lt_f32_e32 vcc, 0, v5
	s_nop 1
	v_cndmask_b32_e32 v5, v12, v13, vcc
	v_mul_f32_e32 v12, 0x37800000, v5
	v_cndmask_b32_e64 v5, v5, v12, s[0:1]
	v_cmp_class_f32_e32 vcc, v4, v199
	s_nop 1
	v_cndmask_b32_e32 v4, v5, v4, vcc
	v_div_scale_f32 v5, s[0:1], v4, v4, 1.0
	v_rcp_f32_e32 v12, v5
	s_nop 0
	v_fma_f32 v13, -v5, v12, 1.0
	v_fmac_f32_e32 v12, v13, v12
	v_div_scale_f32 v13, vcc, 1.0, v4, 1.0
	v_mul_f32_e32 v16, v13, v12
	v_fma_f32 v39, -v5, v16, v13
	v_fmac_f32_e32 v16, v39, v12
	v_fma_f32 v5, -v5, v16, v13
	v_div_fmas_f32 v5, v5, v12, v16
	v_div_fixup_f32 v12, v5, v4, 1.0
	v_mov_b32_e32 v4, v9
	v_mov_b32_e32 v5, v3
	v_mov_b32_e32 v9, v2
	v_pk_mul_f32 v[42:43], v[12:13], v[4:5] op_sel_hi:[0,1]
	v_pk_mul_f32 v[56:57], v[12:13], v[8:9] op_sel_hi:[0,1]
	v_mov_b64_e32 v[2:3], v[88:89]
	v_mov_b64_e32 v[4:5], v[90:91]
	v_mov_b64_e32 v[6:7], v[92:93]
	v_mov_b64_e32 v[8:9], v[94:95]
	v_pk_mul_f32 v[58:59], v[12:13], v[58:59] op_sel_hi:[0,1]
	v_pk_mul_f32 v[12:13], v[12:13], v[14:15] op_sel_hi:[0,1]
	v_mul_f32_e32 v12, v2, v12
	v_mul_f32_e32 v14, v6, v56
	v_bfe_u32 v15, v14, 16, 1
	v_add3_u32 v14, v14, v15, s61
	ds_write_b16_d16_hi v47, v14 offset:34816
	v_bfe_u32 v14, v12, 16, 1
	v_add3_u32 v12, v12, v14, s61
	ds_write_b16_d16_hi v48, v12 offset:35904
	v_mul_f32_e32 v12, v7, v57
	v_bfe_u32 v14, v12, 16, 1
	v_add3_u32 v12, v12, v14, s61
	ds_write_b16_d16_hi v47, v12 offset:35088
	v_mul_f32_e32 v12, v3, v13
	v_bfe_u32 v13, v12, 16, 1
	v_add3_u32 v12, v12, v13, s61
	ds_write_b16_d16_hi v48, v12 offset:36176
	v_mul_f32_e32 v12, v8, v42
	v_bfe_u32 v13, v12, 16, 1
	v_add3_u32 v12, v12, v13, s61
	ds_write_b16_d16_hi v47, v12 offset:35360
	v_mul_f32_e32 v12, v4, v58
	v_bfe_u32 v13, v12, 16, 1
	v_add3_u32 v12, v12, v13, s61
	ds_write_b16_d16_hi v48, v12 offset:36448
	v_mul_f32_e32 v12, v9, v43
	v_bfe_u32 v13, v12, 16, 1
	v_add3_u32 v12, v12, v13, s61
	ds_write_b16_d16_hi v47, v12 offset:35632
	v_mul_f32_e32 v12, v5, v59
	v_bfe_u32 v13, v12, 16, 1
	v_add3_u32 v12, v12, v13, s61
	ds_write_b16_d16_hi v48, v12 offset:36720
	v_mov_b64_e32 v[40:41], v[84:85]
	v_mov_b64_e32 v[42:43], v[86:87]
	v_and_b32_e32 v13, 0xffff0000, v41
	v_and_b32_e32 v12, 0xffff0000, v40
	v_lshlrev_b32_e32 v11, 16, v41
	v_lshlrev_b32_e32 v10, 16, v40
	v_pk_mul_f32 v[14:15], v[12:13], v[12:13]
	v_and_b32_e32 v41, 0xffff0000, v43
	v_and_b32_e32 v40, 0xffff0000, v42
	v_pk_fma_f32 v[56:57], v[10:11], v[10:11], v[14:15]
	v_lshlrev_b32_e32 v15, 16, v43
	v_lshlrev_b32_e32 v14, 16, v42
	v_pk_mul_f32 v[42:43], v[40:41], v[40:41]
	v_add_f32_e32 v16, v56, v57
	v_pk_fma_f32 v[42:43], v[14:15], v[14:15], v[42:43]
	s_nop 0
	v_add_f32_e32 v16, v42, v16
	v_add_f32_e32 v16, v43, v16
	ds_bpermute_b32 v39, v44, v16
	s_waitcnt lgkmcnt(0)
	v_add_f32_e32 v16, v16, v39
	ds_bpermute_b32 v39, v45, v16
	s_waitcnt lgkmcnt(0)
	v_add_f32_e32 v16, v16, v39
	ds_bpermute_b32 v39, v46, v16
	s_waitcnt lgkmcnt(0)
	v_add_f32_e32 v16, v16, v39
	v_fmamk_f32 v16, v16, 0x3c800000, v198
	v_cmp_gt_f32_e32 vcc, s40, v16
	v_mul_f32_e32 v39, 0x4f800000, v16
	s_nop 0
	v_cndmask_b32_e32 v16, v16, v39, vcc
	v_sqrt_f32_e32 v39, v16
	s_nop 0
	v_add_u32_e32 v42, -1, v39
	v_fma_f32 v43, -v42, v39, v16
	v_cmp_ge_f32_e64 s[0:1], 0, v43
	v_add_u32_e32 v43, 1, v39
	s_nop 0
	v_cndmask_b32_e64 v42, v39, v42, s[0:1]
	v_fma_f32 v39, -v43, v39, v16
	v_cmp_lt_f32_e64 s[0:1], 0, v39
	s_nop 1
	v_cndmask_b32_e64 v39, v42, v43, s[0:1]
	v_mul_f32_e32 v42, 0x37800000, v39
	v_cndmask_b32_e32 v39, v39, v42, vcc
	v_cmp_class_f32_e32 vcc, v16, v199
	s_nop 1
	v_cndmask_b32_e32 v16, v39, v16, vcc
	v_div_scale_f32 v39, s[0:1], v16, v16, 1.0
	v_rcp_f32_e32 v42, v39
	s_nop 0
	v_fma_f32 v43, -v39, v42, 1.0
	v_fmac_f32_e32 v42, v43, v42
	v_div_scale_f32 v43, vcc, 1.0, v16, 1.0
	v_mul_f32_e32 v56, v43, v42
	v_fma_f32 v57, -v39, v56, v43
	v_fmac_f32_e32 v56, v57, v42
	v_fma_f32 v39, -v39, v56, v43
	v_div_fmas_f32 v39, v39, v42, v56
	v_div_fixup_f32 v16, v39, v16, 1.0
	v_mov_b32_e32 v42, v11
	v_mov_b32_e32 v11, v12
	v_pk_mul_f32 v[10:11], v[16:17], v[10:11] op_sel_hi:[0,1]
	v_mov_b32_e32 v12, v15
	v_mov_b32_e32 v15, v40
	v_mul_f32_e32 v6, v6, v10
	v_pk_mul_f32 v[14:15], v[16:17], v[14:15] op_sel_hi:[0,1]
	v_bfe_u32 v10, v6, 16, 1
	v_add3_u32 v6, v6, v10, s61
	v_mul_f32_e32 v2, v2, v14
	ds_write_b16_d16_hi v47, v6 offset:34944
	v_bfe_u32 v6, v2, 16, 1
	v_add3_u32 v2, v2, v6, s61
	ds_write_b16_d16_hi v48, v2 offset:36032
	v_mul_f32_e32 v2, v7, v11
	v_bfe_u32 v6, v2, 16, 1
	v_add3_u32 v2, v2, v6, s61
	ds_write_b16_d16_hi v47, v2 offset:35216
	v_mul_f32_e32 v2, v3, v15
	v_mov_b32_e32 v43, v13
	v_bfe_u32 v3, v2, 16, 1
	v_pk_mul_f32 v[42:43], v[16:17], v[42:43] op_sel_hi:[0,1]
	v_add3_u32 v2, v2, v3, s61
	ds_write_b16_d16_hi v48, v2 offset:36304
	v_mul_f32_e32 v2, v8, v42
	v_mov_b32_e32 v13, v41
	v_bfe_u32 v3, v2, 16, 1
	v_pk_mul_f32 v[12:13], v[16:17], v[12:13] op_sel_hi:[0,1]
	v_add3_u32 v2, v2, v3, s61
	ds_write_b16_d16_hi v47, v2 offset:35488
	v_mul_f32_e32 v2, v4, v12
	v_bfe_u32 v3, v2, 16, 1
	v_add3_u32 v2, v2, v3, s61
	ds_write_b16_d16_hi v48, v2 offset:36576
	v_mul_f32_e32 v2, v9, v43
	v_bfe_u32 v3, v2, 16, 1
	v_add3_u32 v2, v2, v3, s61
	ds_write_b16_d16_hi v47, v2 offset:35760
	v_mul_f32_e32 v2, v5, v13
	v_bfe_u32 v3, v2, 16, 1
	v_add3_u32 v2, v2, v3, s61
	ds_write_b16_d16_hi v48, v2 offset:36848
	v_mov_b32_e32 v16, v17
	v_mov_b32_e32 v15, v17
	v_mov_b32_e32 v14, v17
	v_mov_b32_e32 v13, v17
	v_mov_b32_e32 v12, v17
	v_mov_b32_e32 v11, v17
	v_mov_b32_e32 v10, v17
	v_mov_b32_e32 v9, v17
	v_mov_b32_e32 v8, v17
	v_mov_b32_e32 v7, v17
	v_mov_b32_e32 v6, v17
	v_mov_b32_e32 v5, v17
	v_mov_b32_e32 v4, v17
	v_mov_b32_e32 v3, v17
	v_mov_b32_e32 v2, v17
	s_waitcnt lgkmcnt(0)
	s_barrier
	s_and_saveexec_b64 s[0:1], s[44:45]
	s_cbranch_execz .LBB0_291
	v_mov_b32_e32 v2, 0
	s_mov_b64 s[40:41], 0
	v_mov_b32_e32 v39, v51
	v_mov_b32_e32 v40, v50
	v_mov_b32_e32 v41, v49
	v_mov_b32_e32 v3, v2
	v_mov_b32_e32 v4, v2
	v_mov_b32_e32 v5, v2
	v_mov_b32_e32 v6, v2
	v_mov_b32_e32 v7, v2
	v_mov_b32_e32 v8, v2
	v_mov_b32_e32 v9, v2
	v_mov_b32_e32 v10, v2
	v_mov_b32_e32 v11, v2
	v_mov_b32_e32 v12, v2
	v_mov_b32_e32 v13, v2
	v_mov_b32_e32 v14, v2
	v_mov_b32_e32 v15, v2
	v_mov_b32_e32 v16, v2
	v_mov_b32_e32 v17, v2
